# peeled first K-loop iteration in G1/G3 GEMM phases (both layers): first MFMA per accumulator uses C=0, 128 acc-zeroing v_mov removed per unit
# speedup vs baseline: 1.0018x; 1.0018x over previous
.LBB0_117:
	s_ashr_i32 s13, s12, 31
	s_lshl_b64 s[16:17], s[12:13], 19
	s_add_u32 s16, s30, s16
	s_addc_u32 s17, s31, s17
	s_and_b64 s[18:19], s[2:3], exec
	s_cselect_b32 s13, s17, s21
	s_cselect_b32 s37, s16, s20
	s_ashr_i32 s11, s10, 31
	s_lshl_b64 s[18:19], s[10:11], 19
	s_add_u32 s18, s28, s18
	s_addc_u32 s19, s29, s19
	s_and_b64 s[24:25], s[2:3], exec
	s_cselect_b32 s11, s19, s23
	s_cselect_b32 s38, s18, s22
	s_add_u32 s20, s20, 0x40080
	s_addc_u32 s21, s21, 0
	s_add_u32 s39, s22, 0x100
	s_addc_u32 s40, s23, 0
	s_mov_b32 s41, -2
	ds_read_b128 v[170:173], v162
	ds_read_b128 v[174:177], v162 offset:1024
	ds_read_b128 v[178:181], v162 offset:2048
	ds_read_b128 v[182:185], v162 offset:3072
	ds_read_b128 v[186:189], v163
	ds_read_b128 v[190:193], v163 offset:1024
	ds_read_b128 v[194:197], v163 offset:2048
	ds_read_b128 v[198:201], v163 offset:3072
	s_add_u32 s22, s20, 0xfffc0080
	s_addc_u32 s23, s21, -1
	s_cmp_eq_u32 s41, 12
	s_cselect_b32 s25, s13, s23
	s_cselect_b32 s24, s37, s22
	s_cselect_b32 s23, s11, s40
	s_cselect_b32 s22, s38, s39
	v_readfirstlane_b32 s42, v165
	v_lshl_add_u64 v[226:227], s[20:21], 0, v[136:137]
	s_mov_b32 m0, s42
	v_readfirstlane_b32 s42, v166
	ds_read_b128 v[202:205], v164
	ds_read_b128 v[206:209], v164 offset:1024
	ds_read_b128 v[210:213], v164 offset:2048
	ds_read_b128 v[214:217], v164 offset:3072
	ds_read_b128 v[218:221], v164 offset:4096
	ds_read_b128 v[222:225], v164 offset:5120
	ds_read_b128 v[230:233], v164 offset:6144
	ds_read_b128 v[234:237], v164 offset:7168
	global_load_lds_dwordx4 v[226:227], off
	v_lshl_add_u64 v[226:227], s[20:21], 0, v[138:139]
	s_mov_b32 m0, s42
	s_nop 0
	global_load_lds_dwordx4 v[226:227], off
	s_waitcnt vmcnt(8)
	s_waitcnt lgkmcnt(0)
	s_barrier
	s_setprio 1
	s_waitcnt lgkmcnt(0)
	v_mfma_f32_16x16x32_bf16 v[124:127], v[170:173], v[202:205], 0
	v_mfma_f32_16x16x32_bf16 v[120:123], v[178:181], v[202:205], 0
	v_mfma_f32_16x16x32_bf16 v[116:119], v[170:173], v[210:213], 0
	v_mfma_f32_16x16x32_bf16 v[108:111], v[178:181], v[210:213], 0
	v_mfma_f32_16x16x32_bf16 v[100:103], v[170:173], v[218:221], 0
	v_mfma_f32_16x16x32_bf16 v[92:95], v[178:181], v[218:221], 0
	v_mfma_f32_16x16x32_bf16 v[84:87], v[170:173], v[230:233], 0
	v_mfma_f32_16x16x32_bf16 v[76:79], v[178:181], v[230:233], 0
	v_mfma_f32_16x16x32_bf16 v[124:127], v[174:177], v[206:209], v[124:127]
	v_mfma_f32_16x16x32_bf16 v[120:123], v[182:185], v[206:209], v[120:123]
	v_mfma_f32_16x16x32_bf16 v[116:119], v[174:177], v[214:217], v[116:119]
	v_mfma_f32_16x16x32_bf16 v[108:111], v[182:185], v[214:217], v[108:111]
	v_mfma_f32_16x16x32_bf16 v[100:103], v[174:177], v[222:225], v[100:103]
	v_mfma_f32_16x16x32_bf16 v[92:95], v[182:185], v[222:225], v[92:95]
	v_mfma_f32_16x16x32_bf16 v[84:87], v[174:177], v[234:237], v[84:87]
	v_mfma_f32_16x16x32_bf16 v[76:79], v[182:185], v[234:237], v[76:79]
	s_setprio 0
	s_setprio 1
	v_mfma_f32_16x16x32_bf16 v[112:115], v[186:189], v[202:205], 0
	v_mfma_f32_16x16x32_bf16 v[104:107], v[194:197], v[202:205], 0
	v_mfma_f32_16x16x32_bf16 v[96:99], v[186:189], v[210:213], 0
	v_mfma_f32_16x16x32_bf16 v[88:91], v[194:197], v[210:213], 0
	v_mfma_f32_16x16x32_bf16 v[80:83], v[186:189], v[218:221], 0
	v_mfma_f32_16x16x32_bf16 v[72:75], v[194:197], v[218:221], 0
	v_mfma_f32_16x16x32_bf16 v[68:71], v[186:189], v[230:233], 0
	v_mfma_f32_16x16x32_bf16 v[64:67], v[194:197], v[230:233], 0
	v_mfma_f32_16x16x32_bf16 v[112:115], v[190:193], v[206:209], v[112:115]
	v_mfma_f32_16x16x32_bf16 v[104:107], v[198:201], v[206:209], v[104:107]
	v_mfma_f32_16x16x32_bf16 v[96:99], v[190:193], v[214:217], v[96:99]
	v_mfma_f32_16x16x32_bf16 v[88:91], v[198:201], v[214:217], v[88:91]
	v_mfma_f32_16x16x32_bf16 v[80:83], v[190:193], v[222:225], v[80:83]
	v_mfma_f32_16x16x32_bf16 v[72:75], v[198:201], v[222:225], v[72:75]
	v_mfma_f32_16x16x32_bf16 v[68:71], v[190:193], v[234:237], v[68:71]
	v_mfma_f32_16x16x32_bf16 v[64:67], v[198:201], v[234:237], v[64:67]
	s_setprio 0
	s_barrier
	v_readfirstlane_b32 s42, v146
	v_lshl_add_u64 v[226:227], s[22:23], 0, v[130:131]
	s_mov_b32 m0, s42
	v_readfirstlane_b32 s42, v147
	ds_read_b128 v[202:205], v164 offset:16384
	ds_read_b128 v[206:209], v164 offset:17408
	ds_read_b128 v[210:213], v164 offset:18432
	ds_read_b128 v[214:217], v164 offset:19456
	ds_read_b128 v[218:221], v164 offset:20480
	ds_read_b128 v[222:225], v164 offset:21504
	ds_read_b128 v[230:233], v164 offset:22528
	ds_read_b128 v[234:237], v164 offset:23552
	global_load_lds_dwordx4 v[226:227], off
	s_mov_b32 m0, s42
	s_add_u32 s42, s22, 0x40000
	v_lshl_add_u64 v[238:239], s[22:23], 0, v[134:135]
	s_addc_u32 s43, s23, 0
	v_readfirstlane_b32 s44, v148
	global_load_lds_dwordx4 v[238:239], off
	v_lshl_add_u64 v[240:241], s[42:43], 0, v[130:131]
	s_mov_b32 m0, s44
	v_lshl_add_u64 v[242:243], s[24:25], 0, v[132:133]
	global_load_lds_dwordx4 v[240:241], off
	v_lshl_add_u64 v[240:241], s[42:43], 0, v[134:135]
	v_readfirstlane_b32 s42, v149
	s_mov_b32 m0, s42
	v_readfirstlane_b32 s42, v150
	global_load_lds_dwordx4 v[240:241], off
	v_lshl_add_u64 v[240:241], s[24:25], 0, v[128:129]
	s_mov_b32 m0, s42
	v_readfirstlane_b32 s42, v151
	global_load_lds_dwordx4 v[240:241], off
	s_mov_b32 m0, s42
	s_nop 0
	global_load_lds_dwordx4 v[242:243], off
	s_waitcnt vmcnt(8)
	s_waitcnt lgkmcnt(0)
	s_barrier
	s_setprio 1
	s_waitcnt lgkmcnt(0)
	v_mfma_f32_16x16x32_bf16 v[60:63], v[170:173], v[202:205], 0
	v_mfma_f32_16x16x32_bf16 v[56:59], v[178:181], v[202:205], 0
	v_mfma_f32_16x16x32_bf16 v[52:55], v[170:173], v[210:213], 0
	v_mfma_f32_16x16x32_bf16 v[44:47], v[178:181], v[210:213], 0
	v_mfma_f32_16x16x32_bf16 v[36:39], v[170:173], v[218:221], 0
	v_mfma_f32_16x16x32_bf16 v[28:31], v[178:181], v[218:221], 0
	v_mfma_f32_16x16x32_bf16 v[20:23], v[170:173], v[230:233], 0
	v_mfma_f32_16x16x32_bf16 v[12:15], v[178:181], v[230:233], 0
	v_mfma_f32_16x16x32_bf16 v[60:63], v[174:177], v[206:209], v[60:63]
	v_mfma_f32_16x16x32_bf16 v[56:59], v[182:185], v[206:209], v[56:59]
	v_mfma_f32_16x16x32_bf16 v[52:55], v[174:177], v[214:217], v[52:55]
	v_mfma_f32_16x16x32_bf16 v[44:47], v[182:185], v[214:217], v[44:47]
	v_mfma_f32_16x16x32_bf16 v[36:39], v[174:177], v[222:225], v[36:39]
	v_mfma_f32_16x16x32_bf16 v[28:31], v[182:185], v[222:225], v[28:31]
	v_mfma_f32_16x16x32_bf16 v[20:23], v[174:177], v[234:237], v[20:23]
	v_mfma_f32_16x16x32_bf16 v[12:15], v[182:185], v[234:237], v[12:15]
	s_setprio 0
	s_setprio 1
	v_mfma_f32_16x16x32_bf16 v[48:51], v[186:189], v[202:205], 0
	v_mfma_f32_16x16x32_bf16 v[40:43], v[194:197], v[202:205], 0
	v_mfma_f32_16x16x32_bf16 v[32:35], v[186:189], v[210:213], 0
	v_mfma_f32_16x16x32_bf16 v[24:27], v[194:197], v[210:213], 0
	v_mfma_f32_16x16x32_bf16 v[16:19], v[186:189], v[218:221], 0
	v_mfma_f32_16x16x32_bf16 v[8:11], v[194:197], v[218:221], 0
	v_mfma_f32_16x16x32_bf16 v[4:7], v[186:189], v[230:233], 0
	v_mfma_f32_16x16x32_bf16 v[0:3], v[194:197], v[230:233], 0
	v_mfma_f32_16x16x32_bf16 v[48:51], v[190:193], v[206:209], v[48:51]
	v_mfma_f32_16x16x32_bf16 v[40:43], v[198:201], v[206:209], v[40:43]
	v_mfma_f32_16x16x32_bf16 v[32:35], v[190:193], v[214:217], v[32:35]
	v_mfma_f32_16x16x32_bf16 v[24:27], v[198:201], v[214:217], v[24:27]
	v_mfma_f32_16x16x32_bf16 v[16:19], v[190:193], v[222:225], v[16:19]
	v_mfma_f32_16x16x32_bf16 v[8:11], v[198:201], v[222:225], v[8:11]
	v_mfma_f32_16x16x32_bf16 v[4:7], v[190:193], v[234:237], v[4:7]
	v_mfma_f32_16x16x32_bf16 v[0:3], v[198:201], v[234:237], v[0:3]
	s_setprio 0
	s_barrier
	ds_read_b128 v[170:173], v167
	ds_read_b128 v[174:177], v167 offset:1024
	ds_read_b128 v[178:181], v167 offset:2048
	ds_read_b128 v[182:185], v167 offset:3072
	ds_read_b128 v[186:189], v168
	ds_read_b128 v[190:193], v168 offset:1024
	ds_read_b128 v[194:197], v168 offset:2048
	ds_read_b128 v[198:201], v168 offset:3072
	s_add_u32 s24, s24, 0x40000
	s_addc_u32 s25, s25, 0
	v_readfirstlane_b32 s42, v152
	v_lshl_add_u64 v[244:245], s[24:25], 0, v[128:129]
	s_mov_b32 m0, s42
	ds_read_b128 v[202:205], v164 offset:32768
	ds_read_b128 v[206:209], v164 offset:33792
	ds_read_b128 v[210:213], v164 offset:34816
	ds_read_b128 v[214:217], v164 offset:35840
	ds_read_b128 v[218:221], v164 offset:36864
	ds_read_b128 v[222:225], v164 offset:37888
	ds_read_b128 v[230:233], v164 offset:38912
	ds_read_b128 v[234:237], v164 offset:39936
	global_load_lds_dwordx4 v[244:245], off
	v_lshl_add_u64 v[244:245], s[24:25], 0, v[132:133]
	v_readfirstlane_b32 s24, v153
	s_mov_b32 m0, s24
	s_nop 0
	global_load_lds_dwordx4 v[244:245], off
	s_waitcnt vmcnt(8)
	s_waitcnt lgkmcnt(0)
	s_barrier
	s_setprio 1
	s_waitcnt lgkmcnt(0)
	v_mfma_f32_16x16x32_bf16 v[124:127], v[170:173], v[202:205], v[124:127]
	v_mfma_f32_16x16x32_bf16 v[120:123], v[178:181], v[202:205], v[120:123]
	v_mfma_f32_16x16x32_bf16 v[116:119], v[170:173], v[210:213], v[116:119]
	v_mfma_f32_16x16x32_bf16 v[108:111], v[178:181], v[210:213], v[108:111]
	v_mfma_f32_16x16x32_bf16 v[100:103], v[170:173], v[218:221], v[100:103]
	v_mfma_f32_16x16x32_bf16 v[92:95], v[178:181], v[218:221], v[92:95]
	v_mfma_f32_16x16x32_bf16 v[84:87], v[170:173], v[230:233], v[84:87]
	v_mfma_f32_16x16x32_bf16 v[76:79], v[178:181], v[230:233], v[76:79]
	v_mfma_f32_16x16x32_bf16 v[124:127], v[174:177], v[206:209], v[124:127]
	v_mfma_f32_16x16x32_bf16 v[120:123], v[182:185], v[206:209], v[120:123]
	v_mfma_f32_16x16x32_bf16 v[116:119], v[174:177], v[214:217], v[116:119]
	v_mfma_f32_16x16x32_bf16 v[108:111], v[182:185], v[214:217], v[108:111]
	v_mfma_f32_16x16x32_bf16 v[100:103], v[174:177], v[222:225], v[100:103]
	v_mfma_f32_16x16x32_bf16 v[92:95], v[182:185], v[222:225], v[92:95]
	v_mfma_f32_16x16x32_bf16 v[84:87], v[174:177], v[234:237], v[84:87]
	v_mfma_f32_16x16x32_bf16 v[76:79], v[182:185], v[234:237], v[76:79]
	s_setprio 0
	s_setprio 1
	v_mfma_f32_16x16x32_bf16 v[112:115], v[186:189], v[202:205], v[112:115]
	v_mfma_f32_16x16x32_bf16 v[104:107], v[194:197], v[202:205], v[104:107]
	v_mfma_f32_16x16x32_bf16 v[96:99], v[186:189], v[210:213], v[96:99]
	v_mfma_f32_16x16x32_bf16 v[88:91], v[194:197], v[210:213], v[88:91]
	v_mfma_f32_16x16x32_bf16 v[80:83], v[186:189], v[218:221], v[80:83]
	v_mfma_f32_16x16x32_bf16 v[72:75], v[194:197], v[218:221], v[72:75]
	v_mfma_f32_16x16x32_bf16 v[68:71], v[186:189], v[230:233], v[68:71]
	v_mfma_f32_16x16x32_bf16 v[64:67], v[194:197], v[230:233], v[64:67]
	v_mfma_f32_16x16x32_bf16 v[112:115], v[190:193], v[206:209], v[112:115]
	v_mfma_f32_16x16x32_bf16 v[104:107], v[198:201], v[206:209], v[104:107]
	v_mfma_f32_16x16x32_bf16 v[96:99], v[190:193], v[214:217], v[96:99]
	v_mfma_f32_16x16x32_bf16 v[88:91], v[198:201], v[214:217], v[88:91]
	v_mfma_f32_16x16x32_bf16 v[80:83], v[190:193], v[222:225], v[80:83]
	v_mfma_f32_16x16x32_bf16 v[72:75], v[198:201], v[222:225], v[72:75]
	v_mfma_f32_16x16x32_bf16 v[68:71], v[190:193], v[234:237], v[68:71]
	v_mfma_f32_16x16x32_bf16 v[64:67], v[198:201], v[234:237], v[64:67]
	s_setprio 0
	s_barrier
	v_readfirstlane_b32 s24, v154
	v_lshl_add_u64 v[226:227], v[226:227], 0, s[6:7]
	s_mov_b32 m0, s24
	v_readfirstlane_b32 s24, v155
	s_add_u32 s22, s22, 0x40080
	ds_read_b128 v[202:205], v164 offset:49152
	ds_read_b128 v[206:209], v164 offset:50176
	ds_read_b128 v[210:213], v164 offset:51200
	ds_read_b128 v[214:217], v164 offset:52224
	ds_read_b128 v[218:221], v164 offset:53248
	ds_read_b128 v[222:225], v164 offset:54272
	ds_read_b128 v[230:233], v164 offset:55296
	ds_read_b128 v[234:237], v164 offset:56320
	global_load_lds_dwordx4 v[226:227], off
	v_lshl_add_u64 v[226:227], v[238:239], 0, s[6:7]
	s_mov_b32 m0, s24
	s_addc_u32 s23, s23, 0
	v_readfirstlane_b32 s24, v158
	global_load_lds_dwordx4 v[226:227], off
	v_lshl_add_u64 v[226:227], s[22:23], 0, v[130:131]
	s_mov_b32 m0, s24
	s_nop 0
	global_load_lds_dwordx4 v[226:227], off
	v_lshl_add_u64 v[226:227], s[22:23], 0, v[134:135]
	v_readfirstlane_b32 s22, v159
	s_mov_b32 m0, s22
	v_readfirstlane_b32 s22, v156
	global_load_lds_dwordx4 v[226:227], off
	v_lshl_add_u64 v[226:227], v[240:241], 0, s[6:7]
	s_mov_b32 m0, s22
	v_readfirstlane_b32 s22, v157
	global_load_lds_dwordx4 v[226:227], off
	v_lshl_add_u64 v[226:227], v[242:243], 0, s[6:7]
	s_mov_b32 m0, s22
	s_nop 0
	global_load_lds_dwordx4 v[226:227], off
	s_waitcnt vmcnt(8)
	s_waitcnt lgkmcnt(0)
	s_barrier
	s_setprio 1
	s_waitcnt lgkmcnt(0)
	v_mfma_f32_16x16x32_bf16 v[60:63], v[170:173], v[202:205], v[60:63]
	v_mfma_f32_16x16x32_bf16 v[56:59], v[178:181], v[202:205], v[56:59]
	v_mfma_f32_16x16x32_bf16 v[52:55], v[170:173], v[210:213], v[52:55]
	v_mfma_f32_16x16x32_bf16 v[44:47], v[178:181], v[210:213], v[44:47]
	v_mfma_f32_16x16x32_bf16 v[36:39], v[170:173], v[218:221], v[36:39]
	v_mfma_f32_16x16x32_bf16 v[28:31], v[178:181], v[218:221], v[28:31]
	v_mfma_f32_16x16x32_bf16 v[20:23], v[170:173], v[230:233], v[20:23]
	v_mfma_f32_16x16x32_bf16 v[12:15], v[178:181], v[230:233], v[12:15]
	v_mfma_f32_16x16x32_bf16 v[60:63], v[174:177], v[206:209], v[60:63]
	v_mfma_f32_16x16x32_bf16 v[56:59], v[182:185], v[206:209], v[56:59]
	v_mfma_f32_16x16x32_bf16 v[52:55], v[174:177], v[214:217], v[52:55]
	v_mfma_f32_16x16x32_bf16 v[44:47], v[182:185], v[214:217], v[44:47]
	v_mfma_f32_16x16x32_bf16 v[36:39], v[174:177], v[222:225], v[36:39]
	v_mfma_f32_16x16x32_bf16 v[28:31], v[182:185], v[222:225], v[28:31]
	v_mfma_f32_16x16x32_bf16 v[20:23], v[174:177], v[234:237], v[20:23]
	v_mfma_f32_16x16x32_bf16 v[12:15], v[182:185], v[234:237], v[12:15]
	s_setprio 0
	s_setprio 1
	v_mfma_f32_16x16x32_bf16 v[48:51], v[186:189], v[202:205], v[48:51]
	v_mfma_f32_16x16x32_bf16 v[40:43], v[194:197], v[202:205], v[40:43]
	v_mfma_f32_16x16x32_bf16 v[32:35], v[186:189], v[210:213], v[32:35]
	v_mfma_f32_16x16x32_bf16 v[24:27], v[194:197], v[210:213], v[24:27]
	v_mfma_f32_16x16x32_bf16 v[16:19], v[186:189], v[218:221], v[16:19]
	v_mfma_f32_16x16x32_bf16 v[8:11], v[194:197], v[218:221], v[8:11]
	v_mfma_f32_16x16x32_bf16 v[4:7], v[186:189], v[230:233], v[4:7]
	v_mfma_f32_16x16x32_bf16 v[0:3], v[194:197], v[230:233], v[0:3]
	v_mfma_f32_16x16x32_bf16 v[48:51], v[190:193], v[206:209], v[48:51]
	v_mfma_f32_16x16x32_bf16 v[40:43], v[198:201], v[206:209], v[40:43]
	v_mfma_f32_16x16x32_bf16 v[32:35], v[190:193], v[214:217], v[32:35]
	v_mfma_f32_16x16x32_bf16 v[24:27], v[198:201], v[214:217], v[24:27]
	v_mfma_f32_16x16x32_bf16 v[16:19], v[190:193], v[222:225], v[16:19]
	v_mfma_f32_16x16x32_bf16 v[8:11], v[198:201], v[222:225], v[8:11]
	v_mfma_f32_16x16x32_bf16 v[4:7], v[190:193], v[234:237], v[4:7]
	v_mfma_f32_16x16x32_bf16 v[0:3], v[198:201], v[234:237], v[0:3]
	s_setprio 0
	s_barrier
	s_add_i32 s41, s41, 2
	s_add_u32 s20, s20, 0x100
	s_addc_u32 s21, s21, 0
	s_add_u32 s39, s39, 0x100
	s_addc_u32 s40, s40, 0

.LBB0_1300:
	s_ashr_i32 s15, s14, 31
	s_lshl_b64 s[16:17], s[14:15], 19
	s_add_u32 s16, s31, s16
	s_addc_u32 s17, s33, s17
	s_and_b64 s[18:19], s[2:3], exec
	s_cselect_b32 s15, s17, s23
	s_cselect_b32 s38, s16, s22
	s_ashr_i32 s13, s12, 31
	s_lshl_b64 s[18:19], s[12:13], 19
	s_add_u32 s18, s29, s18
	s_addc_u32 s19, s30, s19
	s_and_b64 s[26:27], s[2:3], exec
	s_cselect_b32 s13, s19, s25
	s_cselect_b32 s39, s18, s24
	s_add_u32 s22, s22, 0x40080
	s_addc_u32 s23, s23, 0
	s_add_u32 s40, s24, 0x100
	s_addc_u32 s41, s25, 0
	s_mov_b32 s42, -2
	ds_read_b128 v[170:173], v163
	ds_read_b128 v[174:177], v163 offset:1024
	ds_read_b128 v[178:181], v163 offset:2048
	ds_read_b128 v[182:185], v163 offset:3072
	ds_read_b128 v[186:189], v164
	ds_read_b128 v[190:193], v164 offset:1024
	ds_read_b128 v[194:197], v164 offset:2048
	ds_read_b128 v[198:201], v164 offset:3072
	s_add_u32 s24, s22, 0xfffc0080
	s_addc_u32 s25, s23, -1
	s_cmp_eq_u32 s42, 12
	s_cselect_b32 s27, s15, s25
	s_cselect_b32 s26, s38, s24
	s_cselect_b32 s25, s13, s41
	s_cselect_b32 s24, s39, s40
	v_readfirstlane_b32 s43, v166
	v_lshl_add_u64 v[144:145], s[22:23], 0, v[136:137]
	s_mov_b32 m0, s43
	v_readfirstlane_b32 s43, v167
	ds_read_b128 v[202:205], v165
	ds_read_b128 v[206:209], v165 offset:1024
	ds_read_b128 v[210:213], v165 offset:2048
	ds_read_b128 v[214:217], v165 offset:3072
	ds_read_b128 v[218:221], v165 offset:4096
	ds_read_b128 v[222:225], v165 offset:5120
	ds_read_b128 v[230:233], v165 offset:6144
	ds_read_b128 v[234:237], v165 offset:7168
	global_load_lds_dwordx4 v[144:145], off
	v_lshl_add_u64 v[144:145], s[22:23], 0, v[138:139]
	s_mov_b32 m0, s43
	s_nop 0
	global_load_lds_dwordx4 v[144:145], off
	s_waitcnt vmcnt(8)
	s_waitcnt lgkmcnt(0)
	s_barrier
	s_setprio 1
	s_waitcnt lgkmcnt(0)
	v_mfma_f32_16x16x32_bf16 v[124:127], v[170:173], v[202:205], 0
	v_mfma_f32_16x16x32_bf16 v[120:123], v[178:181], v[202:205], 0
	v_mfma_f32_16x16x32_bf16 v[108:111], v[170:173], v[210:213], 0
	v_mfma_f32_16x16x32_bf16 v[104:107], v[178:181], v[210:213], 0
	v_mfma_f32_16x16x32_bf16 v[92:95], v[170:173], v[218:221], 0
	v_mfma_f32_16x16x32_bf16 v[88:91], v[178:181], v[218:221], 0
	v_mfma_f32_16x16x32_bf16 v[76:79], v[170:173], v[230:233], 0
	v_mfma_f32_16x16x32_bf16 v[72:75], v[178:181], v[230:233], 0
	v_mfma_f32_16x16x32_bf16 v[124:127], v[174:177], v[206:209], v[124:127]
	v_mfma_f32_16x16x32_bf16 v[120:123], v[182:185], v[206:209], v[120:123]
	v_mfma_f32_16x16x32_bf16 v[108:111], v[174:177], v[214:217], v[108:111]
	v_mfma_f32_16x16x32_bf16 v[104:107], v[182:185], v[214:217], v[104:107]
	v_mfma_f32_16x16x32_bf16 v[92:95], v[174:177], v[222:225], v[92:95]
	v_mfma_f32_16x16x32_bf16 v[88:91], v[182:185], v[222:225], v[88:91]
	v_mfma_f32_16x16x32_bf16 v[76:79], v[174:177], v[234:237], v[76:79]
	v_mfma_f32_16x16x32_bf16 v[72:75], v[182:185], v[234:237], v[72:75]
	s_setprio 0
	s_setprio 1
	v_mfma_f32_16x16x32_bf16 v[116:119], v[186:189], v[202:205], 0
	v_mfma_f32_16x16x32_bf16 v[112:115], v[194:197], v[202:205], 0
	v_mfma_f32_16x16x32_bf16 v[100:103], v[186:189], v[210:213], 0
	v_mfma_f32_16x16x32_bf16 v[96:99], v[194:197], v[210:213], 0
	v_mfma_f32_16x16x32_bf16 v[84:87], v[186:189], v[218:221], 0
	v_mfma_f32_16x16x32_bf16 v[80:83], v[194:197], v[218:221], 0
	v_mfma_f32_16x16x32_bf16 v[68:71], v[186:189], v[230:233], 0
	v_mfma_f32_16x16x32_bf16 v[64:67], v[194:197], v[230:233], 0
	v_mfma_f32_16x16x32_bf16 v[116:119], v[190:193], v[206:209], v[116:119]
	v_mfma_f32_16x16x32_bf16 v[112:115], v[198:201], v[206:209], v[112:115]
	v_mfma_f32_16x16x32_bf16 v[100:103], v[190:193], v[214:217], v[100:103]
	v_mfma_f32_16x16x32_bf16 v[96:99], v[198:201], v[214:217], v[96:99]
	v_mfma_f32_16x16x32_bf16 v[84:87], v[190:193], v[222:225], v[84:87]
	v_mfma_f32_16x16x32_bf16 v[80:83], v[198:201], v[222:225], v[80:83]
	v_mfma_f32_16x16x32_bf16 v[68:71], v[190:193], v[234:237], v[68:71]
	v_mfma_f32_16x16x32_bf16 v[64:67], v[198:201], v[234:237], v[64:67]
	s_setprio 0
	s_barrier
	v_readfirstlane_b32 s43, v147
	v_lshl_add_u64 v[144:145], s[24:25], 0, v[130:131]
	s_mov_b32 m0, s43
	v_readfirstlane_b32 s43, v148
	s_add_u32 s44, s24, 0x40000
	ds_read_b128 v[202:205], v165 offset:16384
	ds_read_b128 v[206:209], v165 offset:17408
	ds_read_b128 v[210:213], v165 offset:18432
	ds_read_b128 v[214:217], v165 offset:19456
	ds_read_b128 v[218:221], v165 offset:20480
	ds_read_b128 v[222:225], v165 offset:21504
	ds_read_b128 v[230:233], v165 offset:22528
	ds_read_b128 v[234:237], v165 offset:23552
	global_load_lds_dwordx4 v[144:145], off
	v_lshl_add_u64 v[226:227], s[24:25], 0, v[134:135]
	s_mov_b32 m0, s43
	s_addc_u32 s45, s25, 0
	v_readfirstlane_b32 s43, v149
	global_load_lds_dwordx4 v[226:227], off
	v_lshl_add_u64 v[238:239], s[44:45], 0, v[130:131]
	s_mov_b32 m0, s43
	v_readfirstlane_b32 s43, v150
	global_load_lds_dwordx4 v[238:239], off
	v_lshl_add_u64 v[238:239], s[44:45], 0, v[134:135]
	s_mov_b32 m0, s43
	v_readfirstlane_b32 s43, v151
	global_load_lds_dwordx4 v[238:239], off
	v_lshl_add_u64 v[238:239], s[26:27], 0, v[128:129]
	s_mov_b32 m0, s43
	v_readfirstlane_b32 s43, v152
	global_load_lds_dwordx4 v[238:239], off
	v_lshl_add_u64 v[240:241], s[26:27], 0, v[132:133]
	s_mov_b32 m0, s43
	s_nop 0
	global_load_lds_dwordx4 v[240:241], off
	s_waitcnt vmcnt(8)
	s_waitcnt lgkmcnt(0)
	s_barrier
	s_setprio 1
	s_waitcnt lgkmcnt(0)
	v_mfma_f32_16x16x32_bf16 v[60:63], v[170:173], v[202:205], 0
	v_mfma_f32_16x16x32_bf16 v[56:59], v[178:181], v[202:205], 0
	v_mfma_f32_16x16x32_bf16 v[44:47], v[170:173], v[210:213], 0
	v_mfma_f32_16x16x32_bf16 v[40:43], v[178:181], v[210:213], 0
	v_mfma_f32_16x16x32_bf16 v[28:31], v[170:173], v[218:221], 0
	v_mfma_f32_16x16x32_bf16 v[24:27], v[178:181], v[218:221], 0
	v_mfma_f32_16x16x32_bf16 v[12:15], v[170:173], v[230:233], 0
	v_mfma_f32_16x16x32_bf16 v[8:11], v[178:181], v[230:233], 0
	v_mfma_f32_16x16x32_bf16 v[60:63], v[174:177], v[206:209], v[60:63]
	v_mfma_f32_16x16x32_bf16 v[56:59], v[182:185], v[206:209], v[56:59]
	v_mfma_f32_16x16x32_bf16 v[44:47], v[174:177], v[214:217], v[44:47]
	v_mfma_f32_16x16x32_bf16 v[40:43], v[182:185], v[214:217], v[40:43]
	v_mfma_f32_16x16x32_bf16 v[28:31], v[174:177], v[222:225], v[28:31]
	v_mfma_f32_16x16x32_bf16 v[24:27], v[182:185], v[222:225], v[24:27]
	v_mfma_f32_16x16x32_bf16 v[12:15], v[174:177], v[234:237], v[12:15]
	v_mfma_f32_16x16x32_bf16 v[8:11], v[182:185], v[234:237], v[8:11]
	s_setprio 0
	s_setprio 1
	v_mfma_f32_16x16x32_bf16 v[52:55], v[186:189], v[202:205], 0
	v_mfma_f32_16x16x32_bf16 v[48:51], v[194:197], v[202:205], 0
	v_mfma_f32_16x16x32_bf16 v[36:39], v[186:189], v[210:213], 0
	v_mfma_f32_16x16x32_bf16 v[32:35], v[194:197], v[210:213], 0
	v_mfma_f32_16x16x32_bf16 v[20:23], v[186:189], v[218:221], 0
	v_mfma_f32_16x16x32_bf16 v[16:19], v[194:197], v[218:221], 0
	v_mfma_f32_16x16x32_bf16 v[4:7], v[186:189], v[230:233], 0
	v_mfma_f32_16x16x32_bf16 v[0:3], v[194:197], v[230:233], 0
	v_mfma_f32_16x16x32_bf16 v[52:55], v[190:193], v[206:209], v[52:55]
	v_mfma_f32_16x16x32_bf16 v[48:51], v[198:201], v[206:209], v[48:51]
	v_mfma_f32_16x16x32_bf16 v[36:39], v[190:193], v[214:217], v[36:39]
	v_mfma_f32_16x16x32_bf16 v[32:35], v[198:201], v[214:217], v[32:35]
	v_mfma_f32_16x16x32_bf16 v[20:23], v[190:193], v[222:225], v[20:23]
	v_mfma_f32_16x16x32_bf16 v[16:19], v[198:201], v[222:225], v[16:19]
	v_mfma_f32_16x16x32_bf16 v[4:7], v[190:193], v[234:237], v[4:7]
	v_mfma_f32_16x16x32_bf16 v[0:3], v[198:201], v[234:237], v[0:3]
	s_setprio 0
	s_barrier
	ds_read_b128 v[170:173], v168
	ds_read_b128 v[174:177], v168 offset:1024
	ds_read_b128 v[178:181], v168 offset:2048
	ds_read_b128 v[182:185], v168 offset:3072
	ds_read_b128 v[186:189], v169
	ds_read_b128 v[190:193], v169 offset:1024
	ds_read_b128 v[194:197], v169 offset:2048
	ds_read_b128 v[198:201], v169 offset:3072
	s_add_u32 s26, s26, 0x40000
	s_addc_u32 s27, s27, 0
	v_readfirstlane_b32 s43, v153
	v_lshl_add_u64 v[242:243], s[26:27], 0, v[128:129]
	s_mov_b32 m0, s43
	ds_read_b128 v[202:205], v165 offset:32768
	ds_read_b128 v[206:209], v165 offset:33792
	ds_read_b128 v[210:213], v165 offset:34816
	ds_read_b128 v[214:217], v165 offset:35840
	ds_read_b128 v[218:221], v165 offset:36864
	ds_read_b128 v[222:225], v165 offset:37888
	ds_read_b128 v[230:233], v165 offset:38912
	ds_read_b128 v[234:237], v165 offset:39936
	global_load_lds_dwordx4 v[242:243], off
	v_lshl_add_u64 v[242:243], s[26:27], 0, v[132:133]
	v_readfirstlane_b32 s26, v154
	s_mov_b32 m0, s26
	s_nop 0
	global_load_lds_dwordx4 v[242:243], off
	s_waitcnt vmcnt(8)
	s_waitcnt lgkmcnt(0)
	s_barrier
	s_setprio 1
	s_waitcnt lgkmcnt(0)
	v_mfma_f32_16x16x32_bf16 v[124:127], v[170:173], v[202:205], v[124:127]
	v_mfma_f32_16x16x32_bf16 v[120:123], v[178:181], v[202:205], v[120:123]
	v_mfma_f32_16x16x32_bf16 v[108:111], v[170:173], v[210:213], v[108:111]
	v_mfma_f32_16x16x32_bf16 v[104:107], v[178:181], v[210:213], v[104:107]
	v_mfma_f32_16x16x32_bf16 v[92:95], v[170:173], v[218:221], v[92:95]
	v_mfma_f32_16x16x32_bf16 v[88:91], v[178:181], v[218:221], v[88:91]
	v_mfma_f32_16x16x32_bf16 v[76:79], v[170:173], v[230:233], v[76:79]
	v_mfma_f32_16x16x32_bf16 v[72:75], v[178:181], v[230:233], v[72:75]
	v_mfma_f32_16x16x32_bf16 v[124:127], v[174:177], v[206:209], v[124:127]
	v_mfma_f32_16x16x32_bf16 v[120:123], v[182:185], v[206:209], v[120:123]
	v_mfma_f32_16x16x32_bf16 v[108:111], v[174:177], v[214:217], v[108:111]
	v_mfma_f32_16x16x32_bf16 v[104:107], v[182:185], v[214:217], v[104:107]
	v_mfma_f32_16x16x32_bf16 v[92:95], v[174:177], v[222:225], v[92:95]
	v_mfma_f32_16x16x32_bf16 v[88:91], v[182:185], v[222:225], v[88:91]
	v_mfma_f32_16x16x32_bf16 v[76:79], v[174:177], v[234:237], v[76:79]
	v_mfma_f32_16x16x32_bf16 v[72:75], v[182:185], v[234:237], v[72:75]
	s_setprio 0
	s_setprio 1
	v_mfma_f32_16x16x32_bf16 v[116:119], v[186:189], v[202:205], v[116:119]
	v_mfma_f32_16x16x32_bf16 v[112:115], v[194:197], v[202:205], v[112:115]
	v_mfma_f32_16x16x32_bf16 v[100:103], v[186:189], v[210:213], v[100:103]
	v_mfma_f32_16x16x32_bf16 v[96:99], v[194:197], v[210:213], v[96:99]
	v_mfma_f32_16x16x32_bf16 v[84:87], v[186:189], v[218:221], v[84:87]
	v_mfma_f32_16x16x32_bf16 v[80:83], v[194:197], v[218:221], v[80:83]
	v_mfma_f32_16x16x32_bf16 v[68:71], v[186:189], v[230:233], v[68:71]
	v_mfma_f32_16x16x32_bf16 v[64:67], v[194:197], v[230:233], v[64:67]
	v_mfma_f32_16x16x32_bf16 v[116:119], v[190:193], v[206:209], v[116:119]
	v_mfma_f32_16x16x32_bf16 v[112:115], v[198:201], v[206:209], v[112:115]
	v_mfma_f32_16x16x32_bf16 v[100:103], v[190:193], v[214:217], v[100:103]
	v_mfma_f32_16x16x32_bf16 v[96:99], v[198:201], v[214:217], v[96:99]
	v_mfma_f32_16x16x32_bf16 v[84:87], v[190:193], v[222:225], v[84:87]
	v_mfma_f32_16x16x32_bf16 v[80:83], v[198:201], v[222:225], v[80:83]
	v_mfma_f32_16x16x32_bf16 v[68:71], v[190:193], v[234:237], v[68:71]
	v_mfma_f32_16x16x32_bf16 v[64:67], v[198:201], v[234:237], v[64:67]
	s_setprio 0
	s_barrier
	v_readfirstlane_b32 s26, v155
	v_lshl_add_u64 v[144:145], v[144:145], 0, s[6:7]
	s_mov_b32 m0, s26
	v_readfirstlane_b32 s26, v156
	s_add_u32 s24, s24, 0x40080
	ds_read_b128 v[202:205], v165 offset:49152
	ds_read_b128 v[206:209], v165 offset:50176
	ds_read_b128 v[210:213], v165 offset:51200
	ds_read_b128 v[214:217], v165 offset:52224
	ds_read_b128 v[218:221], v165 offset:53248
	ds_read_b128 v[222:225], v165 offset:54272
	ds_read_b128 v[230:233], v165 offset:55296
	ds_read_b128 v[234:237], v165 offset:56320
	global_load_lds_dwordx4 v[144:145], off
	v_lshl_add_u64 v[144:145], v[226:227], 0, s[6:7]
	s_mov_b32 m0, s26
	s_addc_u32 s25, s25, 0
	v_readfirstlane_b32 s26, v159
	global_load_lds_dwordx4 v[144:145], off
	v_lshl_add_u64 v[144:145], s[24:25], 0, v[130:131]
	s_mov_b32 m0, s26
	s_nop 0
	global_load_lds_dwordx4 v[144:145], off
	v_lshl_add_u64 v[144:145], s[24:25], 0, v[134:135]
	v_readfirstlane_b32 s24, v160
	s_mov_b32 m0, s24
	v_readfirstlane_b32 s24, v157
	global_load_lds_dwordx4 v[144:145], off
	v_lshl_add_u64 v[144:145], v[238:239], 0, s[6:7]
	s_mov_b32 m0, s24
	v_readfirstlane_b32 s24, v158
	global_load_lds_dwordx4 v[144:145], off
	v_lshl_add_u64 v[144:145], v[240:241], 0, s[6:7]
	s_mov_b32 m0, s24
	s_nop 0
	global_load_lds_dwordx4 v[144:145], off
	s_waitcnt vmcnt(8)
	s_waitcnt lgkmcnt(0)
	s_barrier
	s_setprio 1
	s_waitcnt lgkmcnt(0)
	v_mfma_f32_16x16x32_bf16 v[60:63], v[170:173], v[202:205], v[60:63]
	v_mfma_f32_16x16x32_bf16 v[56:59], v[178:181], v[202:205], v[56:59]
	v_mfma_f32_16x16x32_bf16 v[44:47], v[170:173], v[210:213], v[44:47]
	v_mfma_f32_16x16x32_bf16 v[40:43], v[178:181], v[210:213], v[40:43]
	v_mfma_f32_16x16x32_bf16 v[28:31], v[170:173], v[218:221], v[28:31]
	v_mfma_f32_16x16x32_bf16 v[24:27], v[178:181], v[218:221], v[24:27]
	v_mfma_f32_16x16x32_bf16 v[12:15], v[170:173], v[230:233], v[12:15]
	v_mfma_f32_16x16x32_bf16 v[8:11], v[178:181], v[230:233], v[8:11]
	v_mfma_f32_16x16x32_bf16 v[60:63], v[174:177], v[206:209], v[60:63]
	v_mfma_f32_16x16x32_bf16 v[56:59], v[182:185], v[206:209], v[56:59]
	v_mfma_f32_16x16x32_bf16 v[44:47], v[174:177], v[214:217], v[44:47]
	v_mfma_f32_16x16x32_bf16 v[40:43], v[182:185], v[214:217], v[40:43]
	v_mfma_f32_16x16x32_bf16 v[28:31], v[174:177], v[222:225], v[28:31]
	v_mfma_f32_16x16x32_bf16 v[24:27], v[182:185], v[222:225], v[24:27]
	v_mfma_f32_16x16x32_bf16 v[12:15], v[174:177], v[234:237], v[12:15]
	v_mfma_f32_16x16x32_bf16 v[8:11], v[182:185], v[234:237], v[8:11]
	s_setprio 0
	s_setprio 1
	v_mfma_f32_16x16x32_bf16 v[52:55], v[186:189], v[202:205], v[52:55]
	v_mfma_f32_16x16x32_bf16 v[48:51], v[194:197], v[202:205], v[48:51]
	v_mfma_f32_16x16x32_bf16 v[36:39], v[186:189], v[210:213], v[36:39]
	v_mfma_f32_16x16x32_bf16 v[32:35], v[194:197], v[210:213], v[32:35]
	v_mfma_f32_16x16x32_bf16 v[20:23], v[186:189], v[218:221], v[20:23]
	v_mfma_f32_16x16x32_bf16 v[16:19], v[194:197], v[218:221], v[16:19]
	v_mfma_f32_16x16x32_bf16 v[4:7], v[186:189], v[230:233], v[4:7]
	v_mfma_f32_16x16x32_bf16 v[0:3], v[194:197], v[230:233], v[0:3]
	v_mfma_f32_16x16x32_bf16 v[52:55], v[190:193], v[206:209], v[52:55]
	v_mfma_f32_16x16x32_bf16 v[48:51], v[198:201], v[206:209], v[48:51]
	v_mfma_f32_16x16x32_bf16 v[36:39], v[190:193], v[214:217], v[36:39]
	v_mfma_f32_16x16x32_bf16 v[32:35], v[198:201], v[214:217], v[32:35]
	v_mfma_f32_16x16x32_bf16 v[20:23], v[190:193], v[222:225], v[20:23]
	v_mfma_f32_16x16x32_bf16 v[16:19], v[198:201], v[222:225], v[16:19]
	v_mfma_f32_16x16x32_bf16 v[4:7], v[190:193], v[234:237], v[4:7]
	v_mfma_f32_16x16x32_bf16 v[0:3], v[198:201], v[234:237], v[0:3]
	s_setprio 0
	s_barrier
	s_add_i32 s42, s42, 2
	s_add_u32 s22, s22, 0x100
	s_addc_u32 s23, s23, 0
	s_add_u32 s40, s40, 0x100
	s_addc_u32 s41, s41, 0

.LBB0_1626:
	s_ashr_i32 s13, s12, 31
	s_lshl_b64 s[16:17], s[12:13], 19
	s_add_u32 s16, s30, s16
	s_addc_u32 s17, s31, s17
	s_and_b64 s[18:19], s[2:3], exec
	s_cselect_b32 s13, s17, s21
	s_cselect_b32 s37, s16, s20
	s_ashr_i32 s11, s10, 31
	s_lshl_b64 s[18:19], s[10:11], 19
	s_add_u32 s18, s28, s18
	s_addc_u32 s19, s29, s19
	s_and_b64 s[24:25], s[2:3], exec
	s_cselect_b32 s11, s19, s23
	s_cselect_b32 s38, s18, s22
	s_add_u32 s20, s20, 0x40080
	s_addc_u32 s21, s21, 0
	s_add_u32 s39, s22, 0x100
	s_addc_u32 s40, s23, 0
	s_mov_b32 s41, -2
	ds_read_b128 v[170:173], v162
	ds_read_b128 v[174:177], v162 offset:1024
	ds_read_b128 v[178:181], v162 offset:2048
	ds_read_b128 v[182:185], v162 offset:3072
	ds_read_b128 v[186:189], v163
	ds_read_b128 v[190:193], v163 offset:1024
	ds_read_b128 v[194:197], v163 offset:2048
	ds_read_b128 v[198:201], v163 offset:3072
	s_add_u32 s22, s20, 0xfffc0080
	s_addc_u32 s23, s21, -1
	s_cmp_eq_u32 s41, 12
	s_cselect_b32 s25, s13, s23
	s_cselect_b32 s24, s37, s22
	s_cselect_b32 s23, s11, s40
	s_cselect_b32 s22, s38, s39
	v_readfirstlane_b32 s42, v165
	v_lshl_add_u64 v[226:227], s[20:21], 0, v[136:137]
	s_mov_b32 m0, s42
	v_readfirstlane_b32 s42, v166
	ds_read_b128 v[202:205], v164
	ds_read_b128 v[206:209], v164 offset:1024
	ds_read_b128 v[210:213], v164 offset:2048
	ds_read_b128 v[214:217], v164 offset:3072
	ds_read_b128 v[218:221], v164 offset:4096
	ds_read_b128 v[222:225], v164 offset:5120
	ds_read_b128 v[230:233], v164 offset:6144
	ds_read_b128 v[234:237], v164 offset:7168
	global_load_lds_dwordx4 v[226:227], off
	v_lshl_add_u64 v[226:227], s[20:21], 0, v[138:139]
	s_mov_b32 m0, s42
	s_nop 0
	global_load_lds_dwordx4 v[226:227], off
	s_waitcnt vmcnt(8)
	s_waitcnt lgkmcnt(0)
	s_barrier
	s_setprio 1
	s_waitcnt lgkmcnt(0)
	v_mfma_f32_16x16x32_bf16 v[124:127], v[170:173], v[202:205], 0
	v_mfma_f32_16x16x32_bf16 v[120:123], v[178:181], v[202:205], 0
	v_mfma_f32_16x16x32_bf16 v[116:119], v[170:173], v[210:213], 0
	v_mfma_f32_16x16x32_bf16 v[108:111], v[178:181], v[210:213], 0
	v_mfma_f32_16x16x32_bf16 v[100:103], v[170:173], v[218:221], 0
	v_mfma_f32_16x16x32_bf16 v[92:95], v[178:181], v[218:221], 0
	v_mfma_f32_16x16x32_bf16 v[84:87], v[170:173], v[230:233], 0
	v_mfma_f32_16x16x32_bf16 v[76:79], v[178:181], v[230:233], 0
	v_mfma_f32_16x16x32_bf16 v[124:127], v[174:177], v[206:209], v[124:127]
	v_mfma_f32_16x16x32_bf16 v[120:123], v[182:185], v[206:209], v[120:123]
	v_mfma_f32_16x16x32_bf16 v[116:119], v[174:177], v[214:217], v[116:119]
	v_mfma_f32_16x16x32_bf16 v[108:111], v[182:185], v[214:217], v[108:111]
	v_mfma_f32_16x16x32_bf16 v[100:103], v[174:177], v[222:225], v[100:103]
	v_mfma_f32_16x16x32_bf16 v[92:95], v[182:185], v[222:225], v[92:95]
	v_mfma_f32_16x16x32_bf16 v[84:87], v[174:177], v[234:237], v[84:87]
	v_mfma_f32_16x16x32_bf16 v[76:79], v[182:185], v[234:237], v[76:79]
	s_setprio 0
	s_setprio 1
	v_mfma_f32_16x16x32_bf16 v[112:115], v[186:189], v[202:205], 0
	v_mfma_f32_16x16x32_bf16 v[104:107], v[194:197], v[202:205], 0
	v_mfma_f32_16x16x32_bf16 v[96:99], v[186:189], v[210:213], 0
	v_mfma_f32_16x16x32_bf16 v[88:91], v[194:197], v[210:213], 0
	v_mfma_f32_16x16x32_bf16 v[80:83], v[186:189], v[218:221], 0
	v_mfma_f32_16x16x32_bf16 v[72:75], v[194:197], v[218:221], 0
	v_mfma_f32_16x16x32_bf16 v[68:71], v[186:189], v[230:233], 0
	v_mfma_f32_16x16x32_bf16 v[64:67], v[194:197], v[230:233], 0
	v_mfma_f32_16x16x32_bf16 v[112:115], v[190:193], v[206:209], v[112:115]
	v_mfma_f32_16x16x32_bf16 v[104:107], v[198:201], v[206:209], v[104:107]
	v_mfma_f32_16x16x32_bf16 v[96:99], v[190:193], v[214:217], v[96:99]
	v_mfma_f32_16x16x32_bf16 v[88:91], v[198:201], v[214:217], v[88:91]
	v_mfma_f32_16x16x32_bf16 v[80:83], v[190:193], v[222:225], v[80:83]
	v_mfma_f32_16x16x32_bf16 v[72:75], v[198:201], v[222:225], v[72:75]
	v_mfma_f32_16x16x32_bf16 v[68:71], v[190:193], v[234:237], v[68:71]
	v_mfma_f32_16x16x32_bf16 v[64:67], v[198:201], v[234:237], v[64:67]
	s_setprio 0
	s_barrier
	v_readfirstlane_b32 s42, v146
	v_lshl_add_u64 v[226:227], s[22:23], 0, v[130:131]
	s_mov_b32 m0, s42
	v_readfirstlane_b32 s42, v147
	ds_read_b128 v[202:205], v164 offset:16384
	ds_read_b128 v[206:209], v164 offset:17408
	ds_read_b128 v[210:213], v164 offset:18432
	ds_read_b128 v[214:217], v164 offset:19456
	ds_read_b128 v[218:221], v164 offset:20480
	ds_read_b128 v[222:225], v164 offset:21504
	ds_read_b128 v[230:233], v164 offset:22528
	ds_read_b128 v[234:237], v164 offset:23552
	global_load_lds_dwordx4 v[226:227], off
	s_mov_b32 m0, s42
	s_add_u32 s42, s22, 0x40000
	v_lshl_add_u64 v[228:229], s[22:23], 0, v[134:135]
	s_addc_u32 s43, s23, 0
	v_readfirstlane_b32 s44, v148
	global_load_lds_dwordx4 v[228:229], off
	v_lshl_add_u64 v[238:239], s[42:43], 0, v[130:131]
	s_mov_b32 m0, s44
	v_lshl_add_u64 v[240:241], s[24:25], 0, v[132:133]
	global_load_lds_dwordx4 v[238:239], off
	v_lshl_add_u64 v[238:239], s[42:43], 0, v[134:135]
	v_readfirstlane_b32 s42, v149
	s_mov_b32 m0, s42
	v_readfirstlane_b32 s42, v150
	global_load_lds_dwordx4 v[238:239], off
	v_lshl_add_u64 v[238:239], s[24:25], 0, v[128:129]
	s_mov_b32 m0, s42
	v_readfirstlane_b32 s42, v151
	global_load_lds_dwordx4 v[238:239], off
	s_mov_b32 m0, s42
	s_nop 0
	global_load_lds_dwordx4 v[240:241], off
	s_waitcnt vmcnt(8)
	s_waitcnt lgkmcnt(0)
	s_barrier
	s_setprio 1
	s_waitcnt lgkmcnt(0)
	v_mfma_f32_16x16x32_bf16 v[60:63], v[170:173], v[202:205], 0
	v_mfma_f32_16x16x32_bf16 v[56:59], v[178:181], v[202:205], 0
	v_mfma_f32_16x16x32_bf16 v[52:55], v[170:173], v[210:213], 0
	v_mfma_f32_16x16x32_bf16 v[44:47], v[178:181], v[210:213], 0
	v_mfma_f32_16x16x32_bf16 v[36:39], v[170:173], v[218:221], 0
	v_mfma_f32_16x16x32_bf16 v[28:31], v[178:181], v[218:221], 0
	v_mfma_f32_16x16x32_bf16 v[20:23], v[170:173], v[230:233], 0
	v_mfma_f32_16x16x32_bf16 v[12:15], v[178:181], v[230:233], 0
	v_mfma_f32_16x16x32_bf16 v[60:63], v[174:177], v[206:209], v[60:63]
	v_mfma_f32_16x16x32_bf16 v[56:59], v[182:185], v[206:209], v[56:59]
	v_mfma_f32_16x16x32_bf16 v[52:55], v[174:177], v[214:217], v[52:55]
	v_mfma_f32_16x16x32_bf16 v[44:47], v[182:185], v[214:217], v[44:47]
	v_mfma_f32_16x16x32_bf16 v[36:39], v[174:177], v[222:225], v[36:39]
	v_mfma_f32_16x16x32_bf16 v[28:31], v[182:185], v[222:225], v[28:31]
	v_mfma_f32_16x16x32_bf16 v[20:23], v[174:177], v[234:237], v[20:23]
	v_mfma_f32_16x16x32_bf16 v[12:15], v[182:185], v[234:237], v[12:15]
	s_setprio 0
	s_setprio 1
	v_mfma_f32_16x16x32_bf16 v[48:51], v[186:189], v[202:205], 0
	v_mfma_f32_16x16x32_bf16 v[40:43], v[194:197], v[202:205], 0
	v_mfma_f32_16x16x32_bf16 v[32:35], v[186:189], v[210:213], 0
	v_mfma_f32_16x16x32_bf16 v[24:27], v[194:197], v[210:213], 0
	v_mfma_f32_16x16x32_bf16 v[16:19], v[186:189], v[218:221], 0
	v_mfma_f32_16x16x32_bf16 v[8:11], v[194:197], v[218:221], 0
	v_mfma_f32_16x16x32_bf16 v[4:7], v[186:189], v[230:233], 0
	v_mfma_f32_16x16x32_bf16 v[0:3], v[194:197], v[230:233], 0
	v_mfma_f32_16x16x32_bf16 v[48:51], v[190:193], v[206:209], v[48:51]
	v_mfma_f32_16x16x32_bf16 v[40:43], v[198:201], v[206:209], v[40:43]
	v_mfma_f32_16x16x32_bf16 v[32:35], v[190:193], v[214:217], v[32:35]
	v_mfma_f32_16x16x32_bf16 v[24:27], v[198:201], v[214:217], v[24:27]
	v_mfma_f32_16x16x32_bf16 v[16:19], v[190:193], v[222:225], v[16:19]
	v_mfma_f32_16x16x32_bf16 v[8:11], v[198:201], v[222:225], v[8:11]
	v_mfma_f32_16x16x32_bf16 v[4:7], v[190:193], v[234:237], v[4:7]
	v_mfma_f32_16x16x32_bf16 v[0:3], v[198:201], v[234:237], v[0:3]
	s_setprio 0
	s_barrier
	ds_read_b128 v[170:173], v167
	ds_read_b128 v[174:177], v167 offset:1024
	ds_read_b128 v[178:181], v167 offset:2048
	ds_read_b128 v[182:185], v167 offset:3072
	ds_read_b128 v[186:189], v168
	ds_read_b128 v[190:193], v168 offset:1024
	ds_read_b128 v[194:197], v168 offset:2048
	ds_read_b128 v[198:201], v168 offset:3072
	s_add_u32 s24, s24, 0x40000
	s_addc_u32 s25, s25, 0
	v_readfirstlane_b32 s42, v152
	v_lshl_add_u64 v[242:243], s[24:25], 0, v[128:129]
	s_mov_b32 m0, s42
	ds_read_b128 v[202:205], v164 offset:32768
	ds_read_b128 v[206:209], v164 offset:33792
	ds_read_b128 v[210:213], v164 offset:34816
	ds_read_b128 v[214:217], v164 offset:35840
	ds_read_b128 v[218:221], v164 offset:36864
	ds_read_b128 v[222:225], v164 offset:37888
	ds_read_b128 v[230:233], v164 offset:38912
	ds_read_b128 v[234:237], v164 offset:39936
	global_load_lds_dwordx4 v[242:243], off
	v_lshl_add_u64 v[242:243], s[24:25], 0, v[132:133]
	v_readfirstlane_b32 s24, v153
	s_mov_b32 m0, s24
	s_nop 0
	global_load_lds_dwordx4 v[242:243], off
	s_waitcnt vmcnt(8)
	s_waitcnt lgkmcnt(0)
	s_barrier
	s_setprio 1
	s_waitcnt lgkmcnt(0)
	v_mfma_f32_16x16x32_bf16 v[124:127], v[170:173], v[202:205], v[124:127]
	v_mfma_f32_16x16x32_bf16 v[120:123], v[178:181], v[202:205], v[120:123]
	v_mfma_f32_16x16x32_bf16 v[116:119], v[170:173], v[210:213], v[116:119]
	v_mfma_f32_16x16x32_bf16 v[108:111], v[178:181], v[210:213], v[108:111]
	v_mfma_f32_16x16x32_bf16 v[100:103], v[170:173], v[218:221], v[100:103]
	v_mfma_f32_16x16x32_bf16 v[92:95], v[178:181], v[218:221], v[92:95]
	v_mfma_f32_16x16x32_bf16 v[84:87], v[170:173], v[230:233], v[84:87]
	v_mfma_f32_16x16x32_bf16 v[76:79], v[178:181], v[230:233], v[76:79]
	v_mfma_f32_16x16x32_bf16 v[124:127], v[174:177], v[206:209], v[124:127]
	v_mfma_f32_16x16x32_bf16 v[120:123], v[182:185], v[206:209], v[120:123]
	v_mfma_f32_16x16x32_bf16 v[116:119], v[174:177], v[214:217], v[116:119]
	v_mfma_f32_16x16x32_bf16 v[108:111], v[182:185], v[214:217], v[108:111]
	v_mfma_f32_16x16x32_bf16 v[100:103], v[174:177], v[222:225], v[100:103]
	v_mfma_f32_16x16x32_bf16 v[92:95], v[182:185], v[222:225], v[92:95]
	v_mfma_f32_16x16x32_bf16 v[84:87], v[174:177], v[234:237], v[84:87]
	v_mfma_f32_16x16x32_bf16 v[76:79], v[182:185], v[234:237], v[76:79]
	s_setprio 0
	s_setprio 1
	v_mfma_f32_16x16x32_bf16 v[112:115], v[186:189], v[202:205], v[112:115]
	v_mfma_f32_16x16x32_bf16 v[104:107], v[194:197], v[202:205], v[104:107]
	v_mfma_f32_16x16x32_bf16 v[96:99], v[186:189], v[210:213], v[96:99]
	v_mfma_f32_16x16x32_bf16 v[88:91], v[194:197], v[210:213], v[88:91]
	v_mfma_f32_16x16x32_bf16 v[80:83], v[186:189], v[218:221], v[80:83]
	v_mfma_f32_16x16x32_bf16 v[72:75], v[194:197], v[218:221], v[72:75]
	v_mfma_f32_16x16x32_bf16 v[68:71], v[186:189], v[230:233], v[68:71]
	v_mfma_f32_16x16x32_bf16 v[64:67], v[194:197], v[230:233], v[64:67]
	v_mfma_f32_16x16x32_bf16 v[112:115], v[190:193], v[206:209], v[112:115]
	v_mfma_f32_16x16x32_bf16 v[104:107], v[198:201], v[206:209], v[104:107]
	v_mfma_f32_16x16x32_bf16 v[96:99], v[190:193], v[214:217], v[96:99]
	v_mfma_f32_16x16x32_bf16 v[88:91], v[198:201], v[214:217], v[88:91]
	v_mfma_f32_16x16x32_bf16 v[80:83], v[190:193], v[222:225], v[80:83]
	v_mfma_f32_16x16x32_bf16 v[72:75], v[198:201], v[222:225], v[72:75]
	v_mfma_f32_16x16x32_bf16 v[68:71], v[190:193], v[234:237], v[68:71]
	v_mfma_f32_16x16x32_bf16 v[64:67], v[198:201], v[234:237], v[64:67]
	s_setprio 0
	s_barrier
	v_readfirstlane_b32 s24, v154
	v_lshl_add_u64 v[226:227], v[226:227], 0, s[6:7]
	s_mov_b32 m0, s24
	v_readfirstlane_b32 s24, v155
	s_add_u32 s22, s22, 0x40080
	ds_read_b128 v[202:205], v164 offset:49152
	ds_read_b128 v[206:209], v164 offset:50176
	ds_read_b128 v[210:213], v164 offset:51200
	ds_read_b128 v[214:217], v164 offset:52224
	ds_read_b128 v[218:221], v164 offset:53248
	ds_read_b128 v[222:225], v164 offset:54272
	ds_read_b128 v[230:233], v164 offset:55296
	ds_read_b128 v[234:237], v164 offset:56320
	global_load_lds_dwordx4 v[226:227], off
	v_lshl_add_u64 v[226:227], v[228:229], 0, s[6:7]
	s_mov_b32 m0, s24
	s_addc_u32 s23, s23, 0
	v_readfirstlane_b32 s24, v158
	global_load_lds_dwordx4 v[226:227], off
	v_lshl_add_u64 v[226:227], s[22:23], 0, v[130:131]
	s_mov_b32 m0, s24
	s_nop 0
	global_load_lds_dwordx4 v[226:227], off
	v_lshl_add_u64 v[226:227], s[22:23], 0, v[134:135]
	v_readfirstlane_b32 s22, v159
	s_mov_b32 m0, s22
	v_readfirstlane_b32 s22, v156
	global_load_lds_dwordx4 v[226:227], off
	v_lshl_add_u64 v[226:227], v[238:239], 0, s[6:7]
	s_mov_b32 m0, s22
	v_readfirstlane_b32 s22, v157
	global_load_lds_dwordx4 v[226:227], off
	v_lshl_add_u64 v[226:227], v[240:241], 0, s[6:7]
	s_mov_b32 m0, s22
	s_nop 0
	global_load_lds_dwordx4 v[226:227], off
	s_waitcnt vmcnt(8)
	s_waitcnt lgkmcnt(0)
	s_barrier
	s_setprio 1
	s_waitcnt lgkmcnt(0)
	v_mfma_f32_16x16x32_bf16 v[60:63], v[170:173], v[202:205], v[60:63]
	v_mfma_f32_16x16x32_bf16 v[56:59], v[178:181], v[202:205], v[56:59]
	v_mfma_f32_16x16x32_bf16 v[52:55], v[170:173], v[210:213], v[52:55]
	v_mfma_f32_16x16x32_bf16 v[44:47], v[178:181], v[210:213], v[44:47]
	v_mfma_f32_16x16x32_bf16 v[36:39], v[170:173], v[218:221], v[36:39]
	v_mfma_f32_16x16x32_bf16 v[28:31], v[178:181], v[218:221], v[28:31]
	v_mfma_f32_16x16x32_bf16 v[20:23], v[170:173], v[230:233], v[20:23]
	v_mfma_f32_16x16x32_bf16 v[12:15], v[178:181], v[230:233], v[12:15]
	v_mfma_f32_16x16x32_bf16 v[60:63], v[174:177], v[206:209], v[60:63]
	v_mfma_f32_16x16x32_bf16 v[56:59], v[182:185], v[206:209], v[56:59]
	v_mfma_f32_16x16x32_bf16 v[52:55], v[174:177], v[214:217], v[52:55]
	v_mfma_f32_16x16x32_bf16 v[44:47], v[182:185], v[214:217], v[44:47]
	v_mfma_f32_16x16x32_bf16 v[36:39], v[174:177], v[222:225], v[36:39]
	v_mfma_f32_16x16x32_bf16 v[28:31], v[182:185], v[222:225], v[28:31]
	v_mfma_f32_16x16x32_bf16 v[20:23], v[174:177], v[234:237], v[20:23]
	v_mfma_f32_16x16x32_bf16 v[12:15], v[182:185], v[234:237], v[12:15]
	s_setprio 0
	s_setprio 1
	v_mfma_f32_16x16x32_bf16 v[48:51], v[186:189], v[202:205], v[48:51]
	v_mfma_f32_16x16x32_bf16 v[40:43], v[194:197], v[202:205], v[40:43]
	v_mfma_f32_16x16x32_bf16 v[32:35], v[186:189], v[210:213], v[32:35]
	v_mfma_f32_16x16x32_bf16 v[24:27], v[194:197], v[210:213], v[24:27]
	v_mfma_f32_16x16x32_bf16 v[16:19], v[186:189], v[218:221], v[16:19]
	v_mfma_f32_16x16x32_bf16 v[8:11], v[194:197], v[218:221], v[8:11]
	v_mfma_f32_16x16x32_bf16 v[4:7], v[186:189], v[230:233], v[4:7]
	v_mfma_f32_16x16x32_bf16 v[0:3], v[194:197], v[230:233], v[0:3]
	v_mfma_f32_16x16x32_bf16 v[48:51], v[190:193], v[206:209], v[48:51]
	v_mfma_f32_16x16x32_bf16 v[40:43], v[198:201], v[206:209], v[40:43]
	v_mfma_f32_16x16x32_bf16 v[32:35], v[190:193], v[214:217], v[32:35]
	v_mfma_f32_16x16x32_bf16 v[24:27], v[198:201], v[214:217], v[24:27]
	v_mfma_f32_16x16x32_bf16 v[16:19], v[190:193], v[222:225], v[16:19]
	v_mfma_f32_16x16x32_bf16 v[8:11], v[198:201], v[222:225], v[8:11]
	v_mfma_f32_16x16x32_bf16 v[4:7], v[190:193], v[234:237], v[4:7]
	v_mfma_f32_16x16x32_bf16 v[0:3], v[198:201], v[234:237], v[0:3]
	s_setprio 0
	s_barrier
	s_add_i32 s41, s41, 2
	s_add_u32 s20, s20, 0x100
	s_addc_u32 s21, s21, 0
	s_add_u32 s39, s39, 0x100
	s_addc_u32 s40, s40, 0

.LBB0_2728:
	s_ashr_i32 s15, s14, 31
	s_lshl_b64 s[16:17], s[14:15], 19
	s_add_u32 s16, s31, s16
	s_addc_u32 s17, s33, s17
	s_and_b64 s[18:19], s[2:3], exec
	s_cselect_b32 s15, s17, s23
	s_cselect_b32 s38, s16, s22
	s_ashr_i32 s13, s12, 31
	s_lshl_b64 s[18:19], s[12:13], 19
	s_add_u32 s18, s29, s18
	s_addc_u32 s19, s30, s19
	s_and_b64 s[26:27], s[2:3], exec
	s_cselect_b32 s13, s19, s25
	s_cselect_b32 s39, s18, s24
	s_add_u32 s22, s22, 0x40080
	s_addc_u32 s23, s23, 0
	s_add_u32 s40, s24, 0x100
	s_addc_u32 s41, s25, 0
	s_mov_b32 s42, -2
	ds_read_b128 v[170:173], v163
	ds_read_b128 v[174:177], v163 offset:1024
	ds_read_b128 v[178:181], v163 offset:2048
	ds_read_b128 v[182:185], v163 offset:3072
	ds_read_b128 v[186:189], v164
	ds_read_b128 v[190:193], v164 offset:1024
	ds_read_b128 v[194:197], v164 offset:2048
	ds_read_b128 v[198:201], v164 offset:3072
	s_add_u32 s24, s22, 0xfffc0080
	s_addc_u32 s25, s23, -1
	s_cmp_eq_u32 s42, 12
	s_cselect_b32 s27, s15, s25
	s_cselect_b32 s26, s38, s24
	s_cselect_b32 s25, s13, s41
	s_cselect_b32 s24, s39, s40
	v_readfirstlane_b32 s43, v166
	v_lshl_add_u64 v[144:145], s[22:23], 0, v[136:137]
	s_mov_b32 m0, s43
	v_readfirstlane_b32 s43, v167
	ds_read_b128 v[202:205], v165
	ds_read_b128 v[206:209], v165 offset:1024
	ds_read_b128 v[210:213], v165 offset:2048
	ds_read_b128 v[214:217], v165 offset:3072
	ds_read_b128 v[218:221], v165 offset:4096
	ds_read_b128 v[222:225], v165 offset:5120
	ds_read_b128 v[230:233], v165 offset:6144
	ds_read_b128 v[234:237], v165 offset:7168
	global_load_lds_dwordx4 v[144:145], off
	v_lshl_add_u64 v[144:145], s[22:23], 0, v[138:139]
	s_mov_b32 m0, s43
	s_nop 0
	global_load_lds_dwordx4 v[144:145], off
	s_waitcnt vmcnt(8)
	s_waitcnt lgkmcnt(0)
	s_barrier
	s_setprio 1
	s_waitcnt lgkmcnt(0)
	v_mfma_f32_16x16x32_bf16 v[124:127], v[170:173], v[202:205], 0
	v_mfma_f32_16x16x32_bf16 v[120:123], v[178:181], v[202:205], 0
	v_mfma_f32_16x16x32_bf16 v[108:111], v[170:173], v[210:213], 0
	v_mfma_f32_16x16x32_bf16 v[104:107], v[178:181], v[210:213], 0
	v_mfma_f32_16x16x32_bf16 v[92:95], v[170:173], v[218:221], 0
	v_mfma_f32_16x16x32_bf16 v[88:91], v[178:181], v[218:221], 0
	v_mfma_f32_16x16x32_bf16 v[76:79], v[170:173], v[230:233], 0
	v_mfma_f32_16x16x32_bf16 v[72:75], v[178:181], v[230:233], 0
	v_mfma_f32_16x16x32_bf16 v[124:127], v[174:177], v[206:209], v[124:127]
	v_mfma_f32_16x16x32_bf16 v[120:123], v[182:185], v[206:209], v[120:123]
	v_mfma_f32_16x16x32_bf16 v[108:111], v[174:177], v[214:217], v[108:111]
	v_mfma_f32_16x16x32_bf16 v[104:107], v[182:185], v[214:217], v[104:107]
	v_mfma_f32_16x16x32_bf16 v[92:95], v[174:177], v[222:225], v[92:95]
	v_mfma_f32_16x16x32_bf16 v[88:91], v[182:185], v[222:225], v[88:91]
	v_mfma_f32_16x16x32_bf16 v[76:79], v[174:177], v[234:237], v[76:79]
	v_mfma_f32_16x16x32_bf16 v[72:75], v[182:185], v[234:237], v[72:75]
	s_setprio 0
	s_setprio 1
	v_mfma_f32_16x16x32_bf16 v[116:119], v[186:189], v[202:205], 0
	v_mfma_f32_16x16x32_bf16 v[112:115], v[194:197], v[202:205], 0
	v_mfma_f32_16x16x32_bf16 v[100:103], v[186:189], v[210:213], 0
	v_mfma_f32_16x16x32_bf16 v[96:99], v[194:197], v[210:213], 0
	v_mfma_f32_16x16x32_bf16 v[84:87], v[186:189], v[218:221], 0
	v_mfma_f32_16x16x32_bf16 v[80:83], v[194:197], v[218:221], 0
	v_mfma_f32_16x16x32_bf16 v[68:71], v[186:189], v[230:233], 0
	v_mfma_f32_16x16x32_bf16 v[64:67], v[194:197], v[230:233], 0
	v_mfma_f32_16x16x32_bf16 v[116:119], v[190:193], v[206:209], v[116:119]
	v_mfma_f32_16x16x32_bf16 v[112:115], v[198:201], v[206:209], v[112:115]
	v_mfma_f32_16x16x32_bf16 v[100:103], v[190:193], v[214:217], v[100:103]
	v_mfma_f32_16x16x32_bf16 v[96:99], v[198:201], v[214:217], v[96:99]
	v_mfma_f32_16x16x32_bf16 v[84:87], v[190:193], v[222:225], v[84:87]
	v_mfma_f32_16x16x32_bf16 v[80:83], v[198:201], v[222:225], v[80:83]
	v_mfma_f32_16x16x32_bf16 v[68:71], v[190:193], v[234:237], v[68:71]
	v_mfma_f32_16x16x32_bf16 v[64:67], v[198:201], v[234:237], v[64:67]
	s_setprio 0
	s_barrier
	v_readfirstlane_b32 s43, v147
	v_lshl_add_u64 v[144:145], s[24:25], 0, v[130:131]
	s_mov_b32 m0, s43
	v_readfirstlane_b32 s43, v148
	s_add_u32 s44, s24, 0x40000
	ds_read_b128 v[202:205], v165 offset:16384
	ds_read_b128 v[206:209], v165 offset:17408
	ds_read_b128 v[210:213], v165 offset:18432
	ds_read_b128 v[214:217], v165 offset:19456
	ds_read_b128 v[218:221], v165 offset:20480
	ds_read_b128 v[222:225], v165 offset:21504
	ds_read_b128 v[230:233], v165 offset:22528
	ds_read_b128 v[234:237], v165 offset:23552
	global_load_lds_dwordx4 v[144:145], off
	v_lshl_add_u64 v[226:227], s[24:25], 0, v[134:135]
	s_mov_b32 m0, s43
	s_addc_u32 s45, s25, 0
	v_readfirstlane_b32 s43, v149
	global_load_lds_dwordx4 v[226:227], off
	v_lshl_add_u64 v[228:229], s[44:45], 0, v[130:131]
	s_mov_b32 m0, s43
	v_readfirstlane_b32 s43, v150
	global_load_lds_dwordx4 v[228:229], off
	v_lshl_add_u64 v[228:229], s[44:45], 0, v[134:135]
	s_mov_b32 m0, s43
	v_readfirstlane_b32 s43, v151
	global_load_lds_dwordx4 v[228:229], off
	v_lshl_add_u64 v[228:229], s[26:27], 0, v[128:129]
	s_mov_b32 m0, s43
	v_readfirstlane_b32 s43, v152
	global_load_lds_dwordx4 v[228:229], off
	v_lshl_add_u64 v[238:239], s[26:27], 0, v[132:133]
	s_mov_b32 m0, s43
	s_nop 0
	global_load_lds_dwordx4 v[238:239], off
	s_waitcnt vmcnt(8)
	s_waitcnt lgkmcnt(0)
	s_barrier
	s_setprio 1
	s_waitcnt lgkmcnt(0)
	v_mfma_f32_16x16x32_bf16 v[60:63], v[170:173], v[202:205], 0
	v_mfma_f32_16x16x32_bf16 v[56:59], v[178:181], v[202:205], 0
	v_mfma_f32_16x16x32_bf16 v[44:47], v[170:173], v[210:213], 0
	v_mfma_f32_16x16x32_bf16 v[40:43], v[178:181], v[210:213], 0
	v_mfma_f32_16x16x32_bf16 v[28:31], v[170:173], v[218:221], 0
	v_mfma_f32_16x16x32_bf16 v[24:27], v[178:181], v[218:221], 0
	v_mfma_f32_16x16x32_bf16 v[12:15], v[170:173], v[230:233], 0
	v_mfma_f32_16x16x32_bf16 v[8:11], v[178:181], v[230:233], 0
	v_mfma_f32_16x16x32_bf16 v[60:63], v[174:177], v[206:209], v[60:63]
	v_mfma_f32_16x16x32_bf16 v[56:59], v[182:185], v[206:209], v[56:59]
	v_mfma_f32_16x16x32_bf16 v[44:47], v[174:177], v[214:217], v[44:47]
	v_mfma_f32_16x16x32_bf16 v[40:43], v[182:185], v[214:217], v[40:43]
	v_mfma_f32_16x16x32_bf16 v[28:31], v[174:177], v[222:225], v[28:31]
	v_mfma_f32_16x16x32_bf16 v[24:27], v[182:185], v[222:225], v[24:27]
	v_mfma_f32_16x16x32_bf16 v[12:15], v[174:177], v[234:237], v[12:15]
	v_mfma_f32_16x16x32_bf16 v[8:11], v[182:185], v[234:237], v[8:11]
	s_setprio 0
	s_setprio 1
	v_mfma_f32_16x16x32_bf16 v[52:55], v[186:189], v[202:205], 0
	v_mfma_f32_16x16x32_bf16 v[48:51], v[194:197], v[202:205], 0
	v_mfma_f32_16x16x32_bf16 v[36:39], v[186:189], v[210:213], 0
	v_mfma_f32_16x16x32_bf16 v[32:35], v[194:197], v[210:213], 0
	v_mfma_f32_16x16x32_bf16 v[20:23], v[186:189], v[218:221], 0
	v_mfma_f32_16x16x32_bf16 v[16:19], v[194:197], v[218:221], 0
	v_mfma_f32_16x16x32_bf16 v[4:7], v[186:189], v[230:233], 0
	v_mfma_f32_16x16x32_bf16 v[0:3], v[194:197], v[230:233], 0
	v_mfma_f32_16x16x32_bf16 v[52:55], v[190:193], v[206:209], v[52:55]
	v_mfma_f32_16x16x32_bf16 v[48:51], v[198:201], v[206:209], v[48:51]
	v_mfma_f32_16x16x32_bf16 v[36:39], v[190:193], v[214:217], v[36:39]
	v_mfma_f32_16x16x32_bf16 v[32:35], v[198:201], v[214:217], v[32:35]
	v_mfma_f32_16x16x32_bf16 v[20:23], v[190:193], v[222:225], v[20:23]
	v_mfma_f32_16x16x32_bf16 v[16:19], v[198:201], v[222:225], v[16:19]
	v_mfma_f32_16x16x32_bf16 v[4:7], v[190:193], v[234:237], v[4:7]
	v_mfma_f32_16x16x32_bf16 v[0:3], v[198:201], v[234:237], v[0:3]
	s_setprio 0
	s_barrier
	ds_read_b128 v[170:173], v168
	ds_read_b128 v[174:177], v168 offset:1024
	ds_read_b128 v[178:181], v168 offset:2048
	ds_read_b128 v[182:185], v168 offset:3072
	ds_read_b128 v[186:189], v169
	ds_read_b128 v[190:193], v169 offset:1024
	ds_read_b128 v[194:197], v169 offset:2048
	ds_read_b128 v[198:201], v169 offset:3072
	s_add_u32 s26, s26, 0x40000
	s_addc_u32 s27, s27, 0
	v_readfirstlane_b32 s43, v153
	v_lshl_add_u64 v[240:241], s[26:27], 0, v[128:129]
	s_mov_b32 m0, s43
	ds_read_b128 v[202:205], v165 offset:32768
	ds_read_b128 v[206:209], v165 offset:33792
	ds_read_b128 v[210:213], v165 offset:34816
	ds_read_b128 v[214:217], v165 offset:35840
	ds_read_b128 v[218:221], v165 offset:36864
	ds_read_b128 v[222:225], v165 offset:37888
	ds_read_b128 v[230:233], v165 offset:38912
	ds_read_b128 v[234:237], v165 offset:39936
	global_load_lds_dwordx4 v[240:241], off
	v_lshl_add_u64 v[240:241], s[26:27], 0, v[132:133]
	v_readfirstlane_b32 s26, v154
	s_mov_b32 m0, s26
	s_nop 0
	global_load_lds_dwordx4 v[240:241], off
	s_waitcnt vmcnt(8)
	s_waitcnt lgkmcnt(0)
	s_barrier
	s_setprio 1
	s_waitcnt lgkmcnt(0)
	v_mfma_f32_16x16x32_bf16 v[124:127], v[170:173], v[202:205], v[124:127]
	v_mfma_f32_16x16x32_bf16 v[120:123], v[178:181], v[202:205], v[120:123]
	v_mfma_f32_16x16x32_bf16 v[108:111], v[170:173], v[210:213], v[108:111]
	v_mfma_f32_16x16x32_bf16 v[104:107], v[178:181], v[210:213], v[104:107]
	v_mfma_f32_16x16x32_bf16 v[92:95], v[170:173], v[218:221], v[92:95]
	v_mfma_f32_16x16x32_bf16 v[88:91], v[178:181], v[218:221], v[88:91]
	v_mfma_f32_16x16x32_bf16 v[76:79], v[170:173], v[230:233], v[76:79]
	v_mfma_f32_16x16x32_bf16 v[72:75], v[178:181], v[230:233], v[72:75]
	v_mfma_f32_16x16x32_bf16 v[124:127], v[174:177], v[206:209], v[124:127]
	v_mfma_f32_16x16x32_bf16 v[120:123], v[182:185], v[206:209], v[120:123]
	v_mfma_f32_16x16x32_bf16 v[108:111], v[174:177], v[214:217], v[108:111]
	v_mfma_f32_16x16x32_bf16 v[104:107], v[182:185], v[214:217], v[104:107]
	v_mfma_f32_16x16x32_bf16 v[92:95], v[174:177], v[222:225], v[92:95]
	v_mfma_f32_16x16x32_bf16 v[88:91], v[182:185], v[222:225], v[88:91]
	v_mfma_f32_16x16x32_bf16 v[76:79], v[174:177], v[234:237], v[76:79]
	v_mfma_f32_16x16x32_bf16 v[72:75], v[182:185], v[234:237], v[72:75]
	s_setprio 0
	s_setprio 1
	v_mfma_f32_16x16x32_bf16 v[116:119], v[186:189], v[202:205], v[116:119]
	v_mfma_f32_16x16x32_bf16 v[112:115], v[194:197], v[202:205], v[112:115]
	v_mfma_f32_16x16x32_bf16 v[100:103], v[186:189], v[210:213], v[100:103]
	v_mfma_f32_16x16x32_bf16 v[96:99], v[194:197], v[210:213], v[96:99]
	v_mfma_f32_16x16x32_bf16 v[84:87], v[186:189], v[218:221], v[84:87]
	v_mfma_f32_16x16x32_bf16 v[80:83], v[194:197], v[218:221], v[80:83]
	v_mfma_f32_16x16x32_bf16 v[68:71], v[186:189], v[230:233], v[68:71]
	v_mfma_f32_16x16x32_bf16 v[64:67], v[194:197], v[230:233], v[64:67]
	v_mfma_f32_16x16x32_bf16 v[116:119], v[190:193], v[206:209], v[116:119]
	v_mfma_f32_16x16x32_bf16 v[112:115], v[198:201], v[206:209], v[112:115]
	v_mfma_f32_16x16x32_bf16 v[100:103], v[190:193], v[214:217], v[100:103]
	v_mfma_f32_16x16x32_bf16 v[96:99], v[198:201], v[214:217], v[96:99]
	v_mfma_f32_16x16x32_bf16 v[84:87], v[190:193], v[222:225], v[84:87]
	v_mfma_f32_16x16x32_bf16 v[80:83], v[198:201], v[222:225], v[80:83]
	v_mfma_f32_16x16x32_bf16 v[68:71], v[190:193], v[234:237], v[68:71]
	v_mfma_f32_16x16x32_bf16 v[64:67], v[198:201], v[234:237], v[64:67]
	s_setprio 0
	s_barrier
	v_readfirstlane_b32 s26, v155
	v_lshl_add_u64 v[144:145], v[144:145], 0, s[6:7]
	s_mov_b32 m0, s26
	v_readfirstlane_b32 s26, v156
	s_add_u32 s24, s24, 0x40080
	ds_read_b128 v[202:205], v165 offset:49152
	ds_read_b128 v[206:209], v165 offset:50176
	ds_read_b128 v[210:213], v165 offset:51200
	ds_read_b128 v[214:217], v165 offset:52224
	ds_read_b128 v[218:221], v165 offset:53248
	ds_read_b128 v[222:225], v165 offset:54272
	ds_read_b128 v[230:233], v165 offset:55296
	ds_read_b128 v[234:237], v165 offset:56320
	global_load_lds_dwordx4 v[144:145], off
	v_lshl_add_u64 v[144:145], v[226:227], 0, s[6:7]
	s_mov_b32 m0, s26
	s_addc_u32 s25, s25, 0
	v_readfirstlane_b32 s26, v159
	global_load_lds_dwordx4 v[144:145], off
	v_lshl_add_u64 v[144:145], s[24:25], 0, v[130:131]
	s_mov_b32 m0, s26
	s_nop 0
	global_load_lds_dwordx4 v[144:145], off
	v_lshl_add_u64 v[144:145], s[24:25], 0, v[134:135]
	v_readfirstlane_b32 s24, v160
	s_mov_b32 m0, s24
	v_readfirstlane_b32 s24, v157
	global_load_lds_dwordx4 v[144:145], off
	v_lshl_add_u64 v[144:145], v[228:229], 0, s[6:7]
	s_mov_b32 m0, s24
	v_readfirstlane_b32 s24, v158
	global_load_lds_dwordx4 v[144:145], off
	v_lshl_add_u64 v[144:145], v[238:239], 0, s[6:7]
	s_mov_b32 m0, s24
	s_nop 0
	global_load_lds_dwordx4 v[144:145], off
	s_waitcnt vmcnt(8)
	s_waitcnt lgkmcnt(0)
	s_barrier
	s_setprio 1
	s_waitcnt lgkmcnt(0)
	v_mfma_f32_16x16x32_bf16 v[60:63], v[170:173], v[202:205], v[60:63]
	v_mfma_f32_16x16x32_bf16 v[56:59], v[178:181], v[202:205], v[56:59]
	v_mfma_f32_16x16x32_bf16 v[44:47], v[170:173], v[210:213], v[44:47]
	v_mfma_f32_16x16x32_bf16 v[40:43], v[178:181], v[210:213], v[40:43]
	v_mfma_f32_16x16x32_bf16 v[28:31], v[170:173], v[218:221], v[28:31]
	v_mfma_f32_16x16x32_bf16 v[24:27], v[178:181], v[218:221], v[24:27]
	v_mfma_f32_16x16x32_bf16 v[12:15], v[170:173], v[230:233], v[12:15]
	v_mfma_f32_16x16x32_bf16 v[8:11], v[178:181], v[230:233], v[8:11]
	v_mfma_f32_16x16x32_bf16 v[60:63], v[174:177], v[206:209], v[60:63]
	v_mfma_f32_16x16x32_bf16 v[56:59], v[182:185], v[206:209], v[56:59]
	v_mfma_f32_16x16x32_bf16 v[44:47], v[174:177], v[214:217], v[44:47]
	v_mfma_f32_16x16x32_bf16 v[40:43], v[182:185], v[214:217], v[40:43]
	v_mfma_f32_16x16x32_bf16 v[28:31], v[174:177], v[222:225], v[28:31]
	v_mfma_f32_16x16x32_bf16 v[24:27], v[182:185], v[222:225], v[24:27]
	v_mfma_f32_16x16x32_bf16 v[12:15], v[174:177], v[234:237], v[12:15]
	v_mfma_f32_16x16x32_bf16 v[8:11], v[182:185], v[234:237], v[8:11]
	s_setprio 0
	s_setprio 1
	v_mfma_f32_16x16x32_bf16 v[52:55], v[186:189], v[202:205], v[52:55]
	v_mfma_f32_16x16x32_bf16 v[48:51], v[194:197], v[202:205], v[48:51]
	v_mfma_f32_16x16x32_bf16 v[36:39], v[186:189], v[210:213], v[36:39]
	v_mfma_f32_16x16x32_bf16 v[32:35], v[194:197], v[210:213], v[32:35]
	v_mfma_f32_16x16x32_bf16 v[20:23], v[186:189], v[218:221], v[20:23]
	v_mfma_f32_16x16x32_bf16 v[16:19], v[194:197], v[218:221], v[16:19]
	v_mfma_f32_16x16x32_bf16 v[4:7], v[186:189], v[230:233], v[4:7]
	v_mfma_f32_16x16x32_bf16 v[0:3], v[194:197], v[230:233], v[0:3]
	v_mfma_f32_16x16x32_bf16 v[52:55], v[190:193], v[206:209], v[52:55]
	v_mfma_f32_16x16x32_bf16 v[48:51], v[198:201], v[206:209], v[48:51]
	v_mfma_f32_16x16x32_bf16 v[36:39], v[190:193], v[214:217], v[36:39]
	v_mfma_f32_16x16x32_bf16 v[32:35], v[198:201], v[214:217], v[32:35]
	v_mfma_f32_16x16x32_bf16 v[20:23], v[190:193], v[222:225], v[20:23]
	v_mfma_f32_16x16x32_bf16 v[16:19], v[198:201], v[222:225], v[16:19]
	v_mfma_f32_16x16x32_bf16 v[4:7], v[190:193], v[234:237], v[4:7]
	v_mfma_f32_16x16x32_bf16 v[0:3], v[198:201], v[234:237], v[0:3]
	s_setprio 0
	s_barrier
	s_add_i32 s42, s42, 2
	s_add_u32 s22, s22, 0x100
	s_addc_u32 s23, s23, 0
	s_add_u32 s40, s40, 0x100
	s_addc_u32 s41, s41, 0
